# prep stage 5 (first FFN weights, layer-1 modulation, DFT tables) moved from phase 1 into phase 0 with rotated job ranks so the 183 idle phase-0 workgroups do it
# speedup vs baseline: 1.0054x; 1.0054x over previous
.LBB0_1255:
	s_cmpk_eq_i32 s93, 0x100
	s_cselect_b32 s2, 1, 6
	s_cselect_b32 s3, 6, 5
	s_cmp_eq_u32 s17, 0
	s_cselect_b32 s92, 0, 5
	s_cselect_b32 s94, s2, s3
	s_cmpk_eq_i32 s93, 0x100
	s_cbranch_scc0 .Lprep_seq_done
	s_mov_b32 s94, 6
	s_cmp_eq_u32 s17, 0
	s_cselect_b32 s92, 0, 6
.Lprep_seq_done:
	s_branch .LBB0_1258
.LBB0_1256:
	s_movk_i32 s43, 0x1f8
	s_movk_i32 s27, 0x2000
	s_mov_b32 s28, 0x7f800000
	s_mov_b64 s[30:31], 0x1000
.LBB0_1257:
	s_add_i32 s92, s92, 1
	s_cmp_eq_u32 s92, 1
	s_cbranch_scc0 .Lprep_st_ok
	s_cmpk_eq_i32 s93, 0x100
	s_cbranch_scc0 .Lprep_st_ok
	s_mov_b32 s92, 5
.Lprep_st_ok:
.LBB0_1258:
	s_cmp_ge_u32 s92, s94
	s_cbranch_scc1 .LBB0_1369
	v_mov_b32_e32 v80, v135
	s_waitcnt lgkmcnt(0)
	s_mov_b64 s[2:3], s[0:1]
	s_load_dwordx2 s[2:3], s[2:3], 0x88
	s_cmp_lt_i32 s92, 2
	s_mov_b64 s[4:5], -1
	s_cbranch_scc1 .LBB0_1272
	s_mov_b64 s[8:9], -1
	s_mov_b64 s[4:5], 0
	s_cmp_lt_i32 s92, 4
	s_mov_b64 s[6:7], 0
	s_cbranch_scc1 .LBB0_1267
	s_cmp_gt_i32 s92, 4
	s_cbranch_scc0 .LBB0_1265
	s_cmp_eq_u32 s92, 5
	s_mov_b64 s[6:7], -1
	s_cbranch_scc0 .LBB0_1264
	s_mov_b64 s[6:7], 0

.LBB0_1277:
	s_add_i32 s4, s54, s6
	s_add_i32 s97, s4, s63
	s_add_i32 s97, s97, s55
	v_readlane_b32 s4, v254, 42
	s_cmp_eq_u32 s92, 5
	s_cbranch_scc0 .Lprep_rk_a
	s_add_i32 s4, s4, 183
	s_and_b32 s4, s4, 0xff
.Lprep_rk_a:
	s_cmp_ge_i32 s4, s97
	s_cbranch_scc1 .LBB0_1257
	s_waitcnt vmcnt(0)
	v_cvt_f32_i32_e32 v3, v80
	s_mov_b32 s6, 0x3fb8aa3b
	s_movk_i32 s38, 0x400
	v_cmp_gt_i32_e64 s[4:5], s38, v80
	v_mul_f32_e32 v0, 0xbe99999a, v3
	v_mul_f32_e32 v1, 0x3fb8aa3b, v0
	v_fma_f32 v2, v0, s6, -v1
	v_rndne_f32_e32 v4, v1
	v_fmac_f32_e32 v2, 0x32a5705f, v0
	v_sub_f32_e32 v1, v1, v4
	v_add_f32_e32 v1, v1, v2
	v_exp_f32_e32 v1, v1
	v_cvt_i32_f32_e32 v2, v4
	s_mov_b32 s8, 0xc2ce8ed0
	v_writelane_b32 v254, s4, 45
	v_cmp_ngt_f32_e32 vcc, s8, v0
	v_ldexp_f32 v1, v1, v2
	s_mov_b32 s9, 0x42b17218
	v_writelane_b32 v254, s5, 46
	v_cmp_gt_i32_e64 s[4:5], 2, v80
	v_cndmask_b32_e32 v1, 0, v1, vcc
	v_cmp_nlt_f32_e32 vcc, s9, v0
	v_writelane_b32 v254, s4, 47
	v_ashrrev_i32_e32 v81, 31, v80
	v_cndmask_b32_e32 v0, v209, v1, vcc
	v_writelane_b32 v254, s5, 48
	v_fmamk_f32 v128, v0, 0xbf19999a, v196
	s_waitcnt lgkmcnt(0)
	v_lshl_add_u64 v[0:1], v[80:81], 2, s[2:3]
	s_mov_b64 s[4:5], 0x629c000
	v_lshl_add_u64 v[84:85], v[0:1], 0, s[4:5]
	s_movk_i32 s4, 0x1000
	v_cmp_gt_i32_e64 s[4:5], s4, v80
	v_mul_f32_e32 v3, 0x3d000000, v3
	v_mul_f32_e64 v6, |v3|, 0.5
	v_writelane_b32 v254, s4, 49
	v_fract_f32_e32 v7, v6
	v_add_f32_e32 v7, v7, v7
	v_writelane_b32 v254, s5, 50
	s_movk_i32 s4, 0x800
	v_cmp_gt_i32_e64 s[4:5], s4, v80
	v_cmp_neq_f32_e32 vcc, s28, v6
	v_and_b32_e32 v4, 0x7fffffff, v3
	v_writelane_b32 v254, s4, 51
	v_cndmask_b32_e32 v6, 0, v7, vcc
	v_xor_b32_e32 v4, v4, v3
	v_writelane_b32 v254, s5, 52
	v_cmp_gt_i32_e64 s[4:5], s27, v80
	v_cmp_class_f32_e64 s[18:19], v3, s43
	v_add_u32_e32 v88, 0x200, v80
	v_writelane_b32 v254, s4, 53
	s_add_u32 s80, s2, 0x6200000
	v_cmp_gt_u32_e64 s[10:11], s38, v88
	v_writelane_b32 v254, s5, 54
	s_movk_i32 s4, 0x280
	v_cmp_gt_i32_e64 s[4:5], s4, v80
	s_addc_u32 s81, s3, 0
	s_add_u32 s78, s2, 0x6220000
	v_writelane_b32 v254, s4, 55
	s_addc_u32 s79, s3, 0
	s_add_u32 s60, s2, 0x5200000
	v_writelane_b32 v254, s5, 56
	v_cmp_gt_f32_e64 s[4:5], |v3|, 1.0
	v_writelane_b32 v254, s10, 57
	s_addc_u32 s61, s3, 0
	v_cndmask_b32_e64 v6, |v3|, v6, s[4:5]
	v_add_f32_e32 v7, v6, v6
	v_rndne_f32_e32 v7, v7
	v_fmac_f32_e32 v6, -0.5, v7
	v_mul_f32_e32 v8, v6, v6
	v_fmamk_f32 v9, v8, 0x3e75aa41, v134
	v_fmaak_f32 v9, v8, v9, 0x40234736
	v_fmaak_f32 v9, v8, v9, 0xc0a55e0e
	v_mul_f32_e32 v10, v6, v8
	v_mul_f32_e32 v9, v10, v9
	v_cvt_i32_f32_e32 v7, v7
	v_fmac_f32_e32 v9, 0x40490fdb, v6
	v_fmamk_f32 v6, v8, 0x3d4be544, v136
	v_fmaak_f32 v6, v8, v6, 0xbfaad1da
	v_fmaak_f32 v6, v8, v6, 0x4081e0d3
	v_fmaak_f32 v6, v8, v6, 0xc09de9e6
	v_fma_f32 v6, v8, v6, 1.0
	v_and_b32_e32 v8, 1, v7
	v_lshlrev_b32_e32 v10, 30, v7
	v_cmp_eq_u32_e32 vcc, 0, v8
	v_and_b32_e32 v10, 0x80000000, v10
	v_xor_b32_e32 v4, v4, v10
	v_cndmask_b32_e32 v8, v6, v9, vcc
	v_xor_b32_e32 v4, v4, v8
	v_and_b32_e32 v3, 2, v7
	v_cndmask_b32_e64 v152, v207, v4, s[18:19]
	v_cndmask_b32_e64 v4, -v9, v6, vcc
	v_cmp_eq_u32_e32 vcc, 0, v3
	s_mov_b32 s5, 0x3f2aaaab
	v_writelane_b32 v254, s11, 58
	v_cndmask_b32_e64 v3, -v4, v4, vcc
	v_cndmask_b32_e64 v153, v207, v3, s[18:19]
	v_and_b32_e32 v3, 15, v80
	v_cvt_f32_ubyte0_e32 v3, v3
	v_mul_f32_e32 v3, 0x3d800000, v3
	v_cmp_eq_f32_e32 vcc, 0, v3
	v_add_u32_e32 v92, 0x600, v80
	s_add_u32 s64, s2, 0x5a00000
	v_cndmask_b32_e64 v16, v210, 1.0, vcc
	v_frexp_mant_f32_e32 v6, v16
	v_cmp_gt_f32_e32 vcc, s5, v6
	s_mov_b32 s5, 0x3f317218
	v_lshlrev_b32_e32 v154, 1, v80
	v_cndmask_b32_e64 v7, 1.0, 2.0, vcc
	v_mul_f32_e32 v6, v6, v7
	v_add_f32_e32 v9, 1.0, v6
	v_rcp_f32_e32 v14, v9
	v_add_f32_e32 v7, -1.0, v9
	v_sub_f32_e32 v11, v6, v7
	v_add_f32_e32 v7, -1.0, v6
	v_mul_f32_e32 v15, v7, v14
	v_mul_f32_e32 v8, v9, v15
	v_fma_f32 v10, v15, v9, -v8
	v_fmac_f32_e32 v10, v15, v11
	v_add_f32_e32 v6, v8, v10
	v_sub_f32_e32 v9, v7, v6
	v_pk_add_f32 v[12:13], v[6:7], v[8:9] neg_lo:[0,1] neg_hi:[0,1]
	v_mov_b32_e32 v11, v6
	v_pk_add_f32 v[6:7], v[12:13], v[10:11] neg_lo:[0,1] neg_hi:[0,1]
	s_addc_u32 s65, s3, 0
	v_add_f32_e32 v6, v6, v7
	v_add_f32_e32 v6, v9, v6
	v_mul_f32_e32 v7, v14, v6
	v_add_f32_e32 v6, v15, v7
	v_sub_f32_e32 v8, v6, v15
	v_sub_f32_e32 v17, v7, v8
	v_mul_f32_e32 v7, v6, v6
	v_fma_f32 v9, v6, v6, -v7
	v_add_f32_e32 v8, v17, v17
	v_fmac_f32_e32 v9, v6, v8
	v_add_f32_e32 v8, v7, v9
	v_fmamk_f32 v10, v8, 0x3e76c4e1, v197
	v_fmaak_f32 v10, v8, v10, 0x3ecccdef
	v_sub_f32_e32 v7, v8, v7
	v_sub_f32_e32 v18, v9, v7
	v_mul_f32_e32 v7, v8, v10
	v_fma_f32 v9, v8, v10, -v7
	v_fmac_f32_e32 v9, v18, v10
	v_add_f32_e32 v10, v7, v9
	v_add_f32_e32 v11, 0x3f2aaaaa, v10
	v_sub_f32_e32 v7, v10, v7
	v_sub_f32_e32 v7, v9, v7
	v_add_f32_e32 v9, 0xbf2aaaaa, v11
	v_add_f32_e32 v7, 0x31739010, v7
	v_sub_f32_e32 v9, v10, v9
	v_pk_mul_f32 v[12:13], v[6:7], v[8:9]
	v_pk_add_f32 v[14:15], v[6:7], v[8:9]
	v_fma_f32 v10, v8, v6, -v12
	v_fmac_f32_e32 v10, v8, v17
	v_mov_b32_e32 v13, v15
	v_fmac_f32_e32 v10, v18, v6
	v_pk_add_f32 v[8:9], v[12:13], v[10:11]
	v_ldexp_f32 v18, v17, 1
	v_sub_f32_e32 v7, v8, v12
	v_sub_f32_e32 v7, v10, v7
	v_sub_f32_e32 v10, v11, v9
	v_add_f32_e32 v14, v15, v10
	v_pk_mul_f32 v[10:11], v[8:9], v[8:9] op_sel:[0,1] op_sel_hi:[1,0]
	v_cvt_f64_f32_e32 v[12:13], v16
	v_frexp_exp_i32_f64_e32 v11, v[12:13]
	v_subbrev_co_u32_e32 v11, vcc, 0, v11, vcc
	v_cvt_f32_i32_e32 v11, v11
	v_fma_f32 v12, v8, v9, -v10
	v_fmac_f32_e32 v12, v8, v14
	v_fmac_f32_e32 v12, v7, v9
	v_mul_f32_e32 v8, 0x3f317218, v11
	v_fma_f32 v14, v11, s5, -v8
	v_fmac_f32_e32 v14, 0xb102e308, v11
	v_ldexp_f32 v15, v6, 1
	v_add_f32_e32 v9, v10, v12
	v_pk_add_f32 v[6:7], v[8:9], v[14:15]
	v_mov_b32_e32 v16, v9
	v_mov_b32_e32 v17, v7
	v_mov_b32_e32 v11, v15
	v_pk_add_f32 v[10:11], v[16:17], v[10:11] neg_lo:[0,1] neg_hi:[0,1]
	v_mov_b32_e32 v13, v9
	v_pk_add_f32 v[10:11], v[12:13], v[10:11] neg_lo:[0,1] neg_hi:[0,1]
	v_mov_b32_e32 v15, v6
	v_add_f32_e32 v9, v18, v10
	v_add_f32_e32 v9, v9, v11
	v_pk_add_f32 v[10:11], v[6:7], v[8:9] neg_lo:[0,1] neg_hi:[0,1]
	v_pk_add_f32 v[12:13], v[6:7], v[8:9]
	v_mov_b32_e32 v8, v9
	v_mov_b32_e32 v11, v13
	v_pk_add_f32 v[16:17], v[14:15], v[10:11] neg_lo:[0,1] neg_hi:[0,1]
	v_pk_add_f32 v[10:11], v[14:15], v[10:11]
	v_mov_b32_e32 v9, v6
	v_pk_add_f32 v[14:15], v[10:11], v[6:7] op_sel:[1,0] op_sel_hi:[0,1] neg_lo:[0,1] neg_hi:[0,1]
	v_pk_add_f32 v[18:19], v[12:13], v[14:15] op_sel_hi:[1,0] neg_lo:[0,1] neg_hi:[0,1]
	v_mov_b32_e32 v12, v13
	v_mov_b32_e32 v13, v11
	v_pk_mov_b32 v[14:15], v[6:7], v[14:15] op_sel:[1,0]
	v_mov_b32_e32 v18, v16
	v_pk_add_f32 v[12:13], v[12:13], v[14:15] neg_lo:[0,1] neg_hi:[0,1]
	v_mov_b32_e32 v17, v11
	v_pk_add_f32 v[6:7], v[8:9], v[12:13] neg_lo:[0,1] neg_hi:[0,1]
	s_movk_i32 s5, 0x204
	v_pk_add_f32 v[8:9], v[18:19], v[6:7]
	v_ashrrev_i32_e32 v151, 6, v80
	v_pk_add_f32 v[12:13], v[8:9], v[8:9] op_sel:[0,1] op_sel_hi:[1,0]
	v_and_b32_e32 v4, 62, v154
	v_pk_add_f32 v[10:11], v[10:11], v[12:13] op_sel:[1,0] op_sel_hi:[0,1]
	v_mov_b32_e32 v9, v10
	v_pk_add_f32 v[14:15], v[8:9], v[16:17] neg_lo:[0,1] neg_hi:[0,1]
	v_mov_b32_e32 v7, v12
	v_sub_f32_e32 v8, v8, v14
	v_pk_add_f32 v[6:7], v[6:7], v[14:15] neg_lo:[0,1] neg_hi:[0,1]
	v_sub_f32_e32 v8, v16, v8
	v_add_f32_e32 v6, v6, v8
	v_add_f32_e32 v6, v6, v7
	v_add_f32_e32 v7, v10, v6
	v_sub_f32_e32 v8, v7, v10
	v_sub_f32_e32 v6, v6, v8
	v_mul_f32_e32 v8, v3, v7
	v_fma_f32 v7, v3, v7, -v8
	v_fmac_f32_e32 v7, v3, v6
	v_add_f32_e32 v6, v8, v7
	v_cmp_class_f32_e64 vcc, v8, s5
	v_sub_f32_e32 v9, v6, v8
	v_sub_f32_e32 v7, v7, v9
	v_cndmask_b32_e32 v6, v6, v8, vcc
	v_cmp_eq_f32_e32 vcc, s9, v6
	s_add_u32 s88, s2, 0x6240000
	s_addc_u32 s15, s3, 0
	v_cndmask_b32_e32 v8, 0, v211, vcc
	v_sub_f32_e32 v9, v6, v8
	v_mul_f32_e32 v10, 0x3fb8aa3b, v9
	v_fma_f32 v11, v9, s6, -v10
	v_rndne_f32_e32 v12, v10
	v_fmac_f32_e32 v11, 0x32a5705f, v9
	v_sub_f32_e32 v10, v10, v12
	v_add_f32_e32 v10, v10, v11
	v_exp_f32_e32 v10, v10
	v_cvt_i32_f32_e32 v11, v12
	v_cmp_neq_f32_e64 vcc, |v6|, s28
	s_add_u32 s45, s2, 0x4d00000
	v_ashrrev_i32_e32 v131, 5, v80
	v_cndmask_b32_e32 v6, 0, v7, vcc
	v_ldexp_f32 v7, v10, v11
	v_cmp_ngt_f32_e32 vcc, s8, v9
	v_add_f32_e32 v6, v8, v6
	v_lshlrev_b32_e32 v2, 4, v80
	v_cndmask_b32_e32 v7, 0, v7, vcc
	v_cmp_nlt_f32_e32 vcc, s9, v9
	s_addc_u32 s42, s3, 0
	v_lshlrev_b32_e32 v5, 6, v131
	v_cndmask_b32_e32 v7, v209, v7, vcc
	v_fma_f32 v6, v7, v6, v7
	v_cmp_class_f32_e64 vcc, v7, s5
	v_and_b32_e32 v2, 0x1f0, v2
	s_add_u32 s43, s2, 0x4200000
	v_cndmask_b32_e32 v6, v6, v7, vcc
	v_and_b32_e32 v7, 0x7fffffff, v6
	v_div_scale_f32 v8, s[8:9], v7, v7, 1.0
	v_rcp_f32_e32 v9, v8
	v_div_scale_f32 v7, vcc, 1.0, v7, 1.0
	s_movk_i32 s8, 0xfbff
	v_fma_f32 v10, -v8, v9, 1.0
	v_fmac_f32_e32 v9, v10, v9
	v_mul_f32_e32 v10, v7, v9
	v_fma_f32 v11, -v8, v10, v7
	v_fmac_f32_e32 v10, v11, v9
	v_fma_f32 v7, -v8, v10, v7
	v_div_fmas_f32 v7, v7, v9, v10
	v_cmp_neq_f32_e32 vcc, s28, v3
	v_cmp_lt_u32_e64 s[10:11], s8, v80
	v_add_u32_e32 v3, 0x800, v80
	s_movk_i32 s8, 0xfc00
	v_cmp_gt_u32_e64 s[26:27], s38, v3
	v_bfi_b32 v3, s8, v3, v80
	v_add_u32_e32 v94, 0xfffffc00, v3
	v_add_u32_e32 v3, 0xc00, v80
	v_max_i32_e32 v9, 0x600, v80
	v_writelane_b32 v254, s10, 59
	v_cmp_gt_u32_e64 s[30:31], s38, v3
	v_bfi_b32 v3, s8, v3, v80
	v_sub_u32_e32 v9, v9, v80
	v_writelane_b32 v254, s11, 60
	v_cmp_gt_u32_e64 s[10:11], s38, v92
	v_add_u32_e32 v98, 0xfffffc00, v3
	v_add_u32_e32 v3, 0x1000, v80
	v_add_u32_e32 v9, 0x1ff, v9
	s_movk_i32 s9, 0x104
	v_writelane_b32 v254, s10, 61
	v_cmp_gt_u32_e64 s[36:37], s38, v3
	v_bfi_b32 v3, s8, v3, v80
	v_lshrrev_b32_e32 v11, 9, v9
	s_movk_i32 s8, 0x1ff
	v_mad_u32_u24 v155, v4, s9, 0
	v_div_fixup_f32 v6, v7, |v6|, 1.0
	v_writelane_b32 v254, s11, 62
	v_mul_lo_u32 v7, v151, s9
	v_add_u32_e32 v11, 1, v11
	v_cmp_lt_u32_e64 s[8:9], s8, v9
	v_and_b32_e32 v157, 0xfffffe, v11
	v_add_u32_e32 v20, 0, v2
	v_writelane_b32 v254, s8, 63
	v_and_b32_e32 v2, 63, v80
	s_addc_u32 s4, s3, 0
	v_writelane_b32 v255, s9, 0
	v_cmp_ne_u32_e64 s[8:9], v11, v157
	v_add_u32_e32 v96, 0xa00, v80
	v_add_u32_e32 v100, 0xe00, v80
	v_writelane_b32 v255, s8, 1
	v_add_u32_e32 v102, 0xfffffc00, v3
	v_add_u32_e32 v3, 0x1200, v80
	v_writelane_b32 v255, s9, 2
	s_mov_b64 s[8:9], 0x629b000
	v_lshl_add_u64 v[106:107], v[0:1], 0, s[8:9]
	v_mad_i64_i32 v[108:109], s[8:9], v5, s71, 0
	v_lshlrev_b32_e32 v82, 8, v80
	v_lshlrev_b32_e32 v129, 2, v80
	v_lshl_add_u32 v21, v2, 2, 0
	s_add_u32 s5, s2, 0x2c00000
	v_cndmask_b32_e32 v156, 0, v6, vcc
	v_and_b32_e32 v6, 0x3ff, v80
	v_cmp_gt_u32_e64 s[18:19], s38, v80
	v_add_u32_e32 v86, 0xfffffc00, v80
	v_and_b32_e32 v8, 0x3ff, v88
	v_add_u32_e32 v90, 0xfffffe00, v80
	v_and_b32_e32 v10, 0x3ff, v92
	v_and_b32_e32 v12, 0x3ff, v96
	v_cmp_gt_u32_e64 s[28:29], s38, v96
	v_and_b32_e32 v14, 0x3ff, v100
	v_cmp_gt_u32_e64 s[34:35], s38, v100
	v_and_b32_e32 v16, 0x3ff, v3
	v_cmp_gt_u32_e64 s[38:39], s38, v3
	v_mul_lo_u32 v3, v131, s96
	v_and_b32_e32 v0, 31, v80
	v_readlane_b32 s8, v254, 32
	v_ashrrev_i32_e32 v83, 31, v82
	v_add_u32_e32 v130, 0, v129
	v_lshl_add_u32 v150, v131, 8, 0
	v_cmp_gt_i32_e64 s[16:17], 64, v80
	s_movk_i32 s40, 0x1f8
	s_addc_u32 s6, s3, 0
	v_ashrrev_i32_e32 v87, 31, v86
	v_ashrrev_i32_e32 v91, 31, v90
	v_ashrrev_i32_e32 v89, 31, v88
	v_ashrrev_i32_e32 v95, 31, v94
	v_ashrrev_i32_e32 v93, 31, v92
	v_ashrrev_i32_e32 v99, 31, v98
	v_ashrrev_i32_e32 v97, 31, v96
	v_ashrrev_i32_e32 v103, 31, v102
	v_ashrrev_i32_e32 v101, 31, v100
	s_sub_i32 s7, s7, s54
	v_lshl_add_u32 v158, v157, 9, v80
	v_mov_b32_e32 v104, v80
	v_mov_b32_e32 v105, v88
	v_lshl_or_b32 v108, v0, 4, v108
	v_add_u32_e32 v159, s8, v129
	v_lshlrev_b32_e32 v160, 2, v131
	v_lshlrev_b32_e32 v161, 1, v131
	v_lshl_add_u32 v162, v131, 1, v131
	v_lshlrev_b32_e32 v110, 2, v6
	v_lshlrev_b32_e32 v112, 2, v8
	v_lshlrev_b32_e32 v114, 2, v10
	v_lshlrev_b32_e32 v116, 2, v12
	v_lshlrev_b32_e32 v118, 2, v14
	v_lshlrev_b32_e32 v120, 2, v16
	v_add_u32_e32 v163, v20, v3
	v_lshlrev_b32_e32 v122, 2, v2
	v_add_u32_e32 v164, v21, v7
	v_lshlrev_b32_e32 v124, 1, v4
	v_readlane_b32 s8, v254, 42
	s_cmp_eq_u32 s92, 5
	s_cbranch_scc0 .Lprep_rk_b
	s_add_i32 s8, s8, 183
	s_and_b32 s8, s8, 0xff
.Lprep_rk_b:
	s_branch .LBB0_1280
.LBB0_1279:
	s_add_i32 s8, s8, s93
	s_cmp_lt_i32 s8, s97
	s_cbranch_scc0 .LBB0_1256
